# v47 + GEMM K-loops (P1 P5 P7 P8 P10): LDS-DMA loads use SGPR base + 32-bit VGPR offset, 60 of 80 v_lshl_add_u64 removed from the MFMA loops
# speedup vs baseline: 1.0175x; 1.0175x over previous
.LBB0_124:
	ds_read_b128 v[154:157], v168
	ds_read_b128 v[158:161], v168 offset:1024
	ds_read_b128 v[162:165], v168 offset:2048
	ds_read_b128 v[172:175], v168 offset:3072
	ds_read_b128 v[176:179], v169
	ds_read_b128 v[180:183], v169 offset:1024
	ds_read_b128 v[184:187], v169 offset:2048
	ds_read_b128 v[188:191], v169 offset:3072
	s_add_u32 s18, s16, 0xfff00080
	s_addc_u32 s19, s17, -1
	s_cmp_eq_u32 s56, 60
	s_cselect_b32 s23, s15, s19
	s_cselect_b32 s22, s21, s18
	s_cselect_b32 s19, s24, s51
	s_cselect_b32 s18, s25, s49
	s_add_i32 m0, s70, 0xc000
	ds_read_b128 v[192:195], v170
	ds_read_b128 v[196:199], v170 offset:1024
	ds_read_b128 v[200:203], v170 offset:2048
	ds_read_b128 v[204:207], v170 offset:3072
	ds_read_b128 v[208:211], v170 offset:4096
	ds_read_b128 v[212:215], v170 offset:5120
	ds_read_b128 v[216:219], v170 offset:6144
	ds_read_b128 v[220:223], v170 offset:7168
	global_load_lds_dwordx4 v146, s[16:17]
	s_add_i32 m0, s70, 0xe000
	s_nop 0
	global_load_lds_dwordx4 v148, s[16:17]
	s_waitcnt vmcnt(8)
	s_waitcnt lgkmcnt(0)
	s_barrier
	s_setprio 1
	s_waitcnt lgkmcnt(0)
	v_mfma_f32_16x16x32_bf16 v[124:127], v[154:157], v[192:195], v[124:127]
	v_mfma_f32_16x16x32_bf16 v[120:123], v[162:165], v[192:195], v[120:123]
	v_mfma_f32_16x16x32_bf16 v[108:111], v[154:157], v[200:203], v[108:111]
	v_mfma_f32_16x16x32_bf16 v[104:107], v[162:165], v[200:203], v[104:107]
	v_mfma_f32_16x16x32_bf16 v[92:95], v[154:157], v[208:211], v[92:95]
	v_mfma_f32_16x16x32_bf16 v[88:91], v[162:165], v[208:211], v[88:91]
	v_mfma_f32_16x16x32_bf16 v[76:79], v[154:157], v[216:219], v[76:79]
	v_mfma_f32_16x16x32_bf16 v[72:75], v[162:165], v[216:219], v[72:75]
	v_mfma_f32_16x16x32_bf16 v[124:127], v[158:161], v[196:199], v[124:127]
	v_mfma_f32_16x16x32_bf16 v[120:123], v[172:175], v[196:199], v[120:123]
	v_mfma_f32_16x16x32_bf16 v[108:111], v[158:161], v[204:207], v[108:111]
	v_mfma_f32_16x16x32_bf16 v[104:107], v[172:175], v[204:207], v[104:107]
	v_mfma_f32_16x16x32_bf16 v[92:95], v[158:161], v[212:215], v[92:95]
	v_mfma_f32_16x16x32_bf16 v[88:91], v[172:175], v[212:215], v[88:91]
	v_mfma_f32_16x16x32_bf16 v[76:79], v[158:161], v[220:223], v[76:79]
	v_mfma_f32_16x16x32_bf16 v[72:75], v[172:175], v[220:223], v[72:75]
	s_setprio 0
	s_setprio 1
	v_mfma_f32_16x16x32_bf16 v[116:119], v[176:179], v[192:195], v[116:119]
	v_mfma_f32_16x16x32_bf16 v[112:115], v[184:187], v[192:195], v[112:115]
	v_mfma_f32_16x16x32_bf16 v[100:103], v[176:179], v[200:203], v[100:103]
	v_mfma_f32_16x16x32_bf16 v[96:99], v[184:187], v[200:203], v[96:99]
	v_mfma_f32_16x16x32_bf16 v[84:87], v[176:179], v[208:211], v[84:87]
	v_mfma_f32_16x16x32_bf16 v[80:83], v[184:187], v[208:211], v[80:83]
	v_mfma_f32_16x16x32_bf16 v[68:71], v[176:179], v[216:219], v[68:71]
	v_mfma_f32_16x16x32_bf16 v[64:67], v[184:187], v[216:219], v[64:67]
	v_mfma_f32_16x16x32_bf16 v[116:119], v[180:183], v[196:199], v[116:119]
	v_mfma_f32_16x16x32_bf16 v[112:115], v[188:191], v[196:199], v[112:115]
	v_mfma_f32_16x16x32_bf16 v[100:103], v[180:183], v[204:207], v[100:103]
	v_mfma_f32_16x16x32_bf16 v[96:99], v[188:191], v[204:207], v[96:99]
	v_mfma_f32_16x16x32_bf16 v[84:87], v[180:183], v[212:215], v[84:87]
	v_mfma_f32_16x16x32_bf16 v[80:83], v[188:191], v[212:215], v[80:83]
	v_mfma_f32_16x16x32_bf16 v[68:71], v[180:183], v[220:223], v[68:71]
	v_mfma_f32_16x16x32_bf16 v[64:67], v[188:191], v[220:223], v[64:67]
	s_setprio 0
	s_barrier
	s_add_i32 s57, s77, s93
	s_mov_b32 m0, s57
	ds_read_b128 v[192:195], v170 offset:16384
	ds_read_b128 v[196:199], v170 offset:17408
	ds_read_b128 v[200:203], v170 offset:18432
	ds_read_b128 v[204:207], v170 offset:19456
	ds_read_b128 v[208:211], v170 offset:20480
	ds_read_b128 v[212:215], v170 offset:21504
	ds_read_b128 v[216:219], v170 offset:22528
	ds_read_b128 v[220:223], v170 offset:23552
	global_load_lds_dwordx4 v130, s[18:19]
	s_add_i32 m0, s57, 0x2000
	s_add_u32 s58, s18, 0x100000
	v_lshl_add_u64 v[224:225], s[18:19], 0, v[134:135]
	s_addc_u32 s59, s19, 0
	s_add_i32 s57, s78, s93
	global_load_lds_dwordx4 v134, s[18:19]
	s_mov_b32 m0, s57
	v_lshl_add_u64 v[228:229], s[22:23], 0, v[132:133]
	global_load_lds_dwordx4 v130, s[58:59]
	s_add_i32 m0, s57, 0x2000
	s_nop 0
	global_load_lds_dwordx4 v134, s[58:59]
	v_lshl_add_u64 v[226:227], s[22:23], 0, v[128:129]
	s_mov_b32 m0, s70
	s_nop 0
	global_load_lds_dwordx4 v128, s[22:23]
	s_mov_b32 m0, s71
	s_nop 0
	global_load_lds_dwordx4 v132, s[22:23]
	s_waitcnt vmcnt(8)
	s_waitcnt lgkmcnt(0)
	s_barrier
	s_setprio 1
	s_waitcnt lgkmcnt(0)
	v_mfma_f32_16x16x32_bf16 v[60:63], v[154:157], v[192:195], v[60:63]
	v_mfma_f32_16x16x32_bf16 v[56:59], v[162:165], v[192:195], v[56:59]
	v_mfma_f32_16x16x32_bf16 v[44:47], v[154:157], v[200:203], v[44:47]
	v_mfma_f32_16x16x32_bf16 v[40:43], v[162:165], v[200:203], v[40:43]
	v_mfma_f32_16x16x32_bf16 v[28:31], v[154:157], v[208:211], v[28:31]
	v_mfma_f32_16x16x32_bf16 v[24:27], v[162:165], v[208:211], v[24:27]
	v_mfma_f32_16x16x32_bf16 v[12:15], v[154:157], v[216:219], v[12:15]
	v_mfma_f32_16x16x32_bf16 v[8:11], v[162:165], v[216:219], v[8:11]
	v_mfma_f32_16x16x32_bf16 v[60:63], v[158:161], v[196:199], v[60:63]
	v_mfma_f32_16x16x32_bf16 v[56:59], v[172:175], v[196:199], v[56:59]
	v_mfma_f32_16x16x32_bf16 v[44:47], v[158:161], v[204:207], v[44:47]
	v_mfma_f32_16x16x32_bf16 v[40:43], v[172:175], v[204:207], v[40:43]
	v_mfma_f32_16x16x32_bf16 v[28:31], v[158:161], v[212:215], v[28:31]
	v_mfma_f32_16x16x32_bf16 v[24:27], v[172:175], v[212:215], v[24:27]
	v_mfma_f32_16x16x32_bf16 v[12:15], v[158:161], v[220:223], v[12:15]
	v_mfma_f32_16x16x32_bf16 v[8:11], v[172:175], v[220:223], v[8:11]
	s_setprio 0
	s_setprio 1
	v_mfma_f32_16x16x32_bf16 v[52:55], v[176:179], v[192:195], v[52:55]
	v_mfma_f32_16x16x32_bf16 v[48:51], v[184:187], v[192:195], v[48:51]
	v_mfma_f32_16x16x32_bf16 v[36:39], v[176:179], v[200:203], v[36:39]
	v_mfma_f32_16x16x32_bf16 v[32:35], v[184:187], v[200:203], v[32:35]
	v_mfma_f32_16x16x32_bf16 v[20:23], v[176:179], v[208:211], v[20:23]
	v_mfma_f32_16x16x32_bf16 v[16:19], v[184:187], v[208:211], v[16:19]
	v_mfma_f32_16x16x32_bf16 v[4:7], v[176:179], v[216:219], v[4:7]
	v_mfma_f32_16x16x32_bf16 v[0:3], v[184:187], v[216:219], v[0:3]
	v_mfma_f32_16x16x32_bf16 v[52:55], v[180:183], v[196:199], v[52:55]
	v_mfma_f32_16x16x32_bf16 v[48:51], v[188:191], v[196:199], v[48:51]
	v_mfma_f32_16x16x32_bf16 v[36:39], v[180:183], v[204:207], v[36:39]
	v_mfma_f32_16x16x32_bf16 v[32:35], v[188:191], v[204:207], v[32:35]
	v_mfma_f32_16x16x32_bf16 v[20:23], v[180:183], v[212:215], v[20:23]
	v_mfma_f32_16x16x32_bf16 v[16:19], v[188:191], v[212:215], v[16:19]
	v_mfma_f32_16x16x32_bf16 v[4:7], v[180:183], v[220:223], v[4:7]
	v_mfma_f32_16x16x32_bf16 v[0:3], v[188:191], v[220:223], v[0:3]
	s_setprio 0
	s_barrier
	s_add_i32 s57, 0, 0x18000
	v_add_u32_e32 v171, s57, v141
	s_add_i32 s58, 0, 0x1c000
	ds_read_b128 v[154:157], v171
	ds_read_b128 v[158:161], v171 offset:1024
	ds_read_b128 v[162:165], v171 offset:2048
	ds_read_b128 v[172:175], v171 offset:3072
	v_add_u32_e32 v171, s58, v141
	ds_read_b128 v[176:179], v171
	ds_read_b128 v[180:183], v171 offset:1024
	ds_read_b128 v[184:187], v171 offset:2048
	ds_read_b128 v[188:191], v171 offset:3072
	s_add_u32 s22, s22, 0x100000
	s_addc_u32 s23, s23, 0
	s_mov_b32 m0, s72
	ds_read_b128 v[192:195], v170 offset:32768
	ds_read_b128 v[196:199], v170 offset:33792
	ds_read_b128 v[200:203], v170 offset:34816
	ds_read_b128 v[204:207], v170 offset:35840
	ds_read_b128 v[208:211], v170 offset:36864
	ds_read_b128 v[212:215], v170 offset:37888
	ds_read_b128 v[216:219], v170 offset:38912
	ds_read_b128 v[220:223], v170 offset:39936
	global_load_lds_dwordx4 v128, s[22:23]
	s_mov_b32 m0, s73
	s_nop 0
	global_load_lds_dwordx4 v132, s[22:23]
	s_waitcnt vmcnt(8)
	s_waitcnt lgkmcnt(0)
	s_barrier
	s_setprio 1
	s_waitcnt lgkmcnt(0)
	v_mfma_f32_16x16x32_bf16 v[124:127], v[154:157], v[192:195], v[124:127]
	v_mfma_f32_16x16x32_bf16 v[120:123], v[162:165], v[192:195], v[120:123]
	v_mfma_f32_16x16x32_bf16 v[108:111], v[154:157], v[200:203], v[108:111]
	v_mfma_f32_16x16x32_bf16 v[104:107], v[162:165], v[200:203], v[104:107]
	v_mfma_f32_16x16x32_bf16 v[92:95], v[154:157], v[208:211], v[92:95]
	v_mfma_f32_16x16x32_bf16 v[88:91], v[162:165], v[208:211], v[88:91]
	v_mfma_f32_16x16x32_bf16 v[76:79], v[154:157], v[216:219], v[76:79]
	v_mfma_f32_16x16x32_bf16 v[72:75], v[162:165], v[216:219], v[72:75]
	v_mfma_f32_16x16x32_bf16 v[124:127], v[158:161], v[196:199], v[124:127]
	v_mfma_f32_16x16x32_bf16 v[120:123], v[172:175], v[196:199], v[120:123]
	v_mfma_f32_16x16x32_bf16 v[108:111], v[158:161], v[204:207], v[108:111]
	v_mfma_f32_16x16x32_bf16 v[104:107], v[172:175], v[204:207], v[104:107]
	v_mfma_f32_16x16x32_bf16 v[92:95], v[158:161], v[212:215], v[92:95]
	v_mfma_f32_16x16x32_bf16 v[88:91], v[172:175], v[212:215], v[88:91]
	v_mfma_f32_16x16x32_bf16 v[76:79], v[158:161], v[220:223], v[76:79]
	v_mfma_f32_16x16x32_bf16 v[72:75], v[172:175], v[220:223], v[72:75]
	s_setprio 0
	s_setprio 1
	v_mfma_f32_16x16x32_bf16 v[116:119], v[176:179], v[192:195], v[116:119]
	v_mfma_f32_16x16x32_bf16 v[112:115], v[184:187], v[192:195], v[112:115]
	v_mfma_f32_16x16x32_bf16 v[100:103], v[176:179], v[200:203], v[100:103]
	v_mfma_f32_16x16x32_bf16 v[96:99], v[184:187], v[200:203], v[96:99]
	v_mfma_f32_16x16x32_bf16 v[84:87], v[176:179], v[208:211], v[84:87]
	v_mfma_f32_16x16x32_bf16 v[80:83], v[184:187], v[208:211], v[80:83]
	v_mfma_f32_16x16x32_bf16 v[68:71], v[176:179], v[216:219], v[68:71]
	v_mfma_f32_16x16x32_bf16 v[64:67], v[184:187], v[216:219], v[64:67]
	v_mfma_f32_16x16x32_bf16 v[116:119], v[180:183], v[196:199], v[116:119]
	v_mfma_f32_16x16x32_bf16 v[112:115], v[188:191], v[196:199], v[112:115]
	v_mfma_f32_16x16x32_bf16 v[100:103], v[180:183], v[204:207], v[100:103]
	v_mfma_f32_16x16x32_bf16 v[96:99], v[188:191], v[204:207], v[96:99]
	v_mfma_f32_16x16x32_bf16 v[84:87], v[180:183], v[212:215], v[84:87]
	v_mfma_f32_16x16x32_bf16 v[80:83], v[188:191], v[212:215], v[80:83]
	v_mfma_f32_16x16x32_bf16 v[68:71], v[180:183], v[220:223], v[68:71]
	v_mfma_f32_16x16x32_bf16 v[64:67], v[188:191], v[220:223], v[64:67]
	s_setprio 0
	s_barrier
	s_add_i32 s22, s57, s93
	s_add_i32 m0, s22, 0xffffff80
	ds_read_b128 v[192:195], v170 offset:49152
	ds_read_b128 v[196:199], v170 offset:50176
	ds_read_b128 v[200:203], v170 offset:51200
	ds_read_b128 v[204:207], v170 offset:52224
	ds_read_b128 v[208:211], v170 offset:53248
	ds_read_b128 v[212:215], v170 offset:54272
	ds_read_b128 v[216:219], v170 offset:55296
	ds_read_b128 v[220:223], v170 offset:56320
	global_load_lds_dwordx4 v130, s[18:19] offset:128
	s_add_i32 m0, s22, 0x2000
	s_add_u32 s18, s18, 0x100080
	v_lshl_add_u64 v[166:167], v[224:225], 0, s[26:27]
	s_addc_u32 s19, s19, 0
	s_add_i32 s22, s58, s93
	global_load_lds_dwordx4 v[166:167], off
	s_mov_b32 m0, s22
	s_nop 0
	global_load_lds_dwordx4 v130, s[18:19]
	s_add_i32 m0, s22, 0x2000
	s_nop 0
	global_load_lds_dwordx4 v134, s[18:19]
	v_lshl_add_u64 v[166:167], v[226:227], 0, s[26:27]
	s_mov_b32 m0, s75
	s_nop 0
	global_load_lds_dwordx4 v[166:167], off
	v_lshl_add_u64 v[166:167], v[228:229], 0, s[26:27]
	s_mov_b32 m0, s76
	s_nop 0
	global_load_lds_dwordx4 v[166:167], off
	s_waitcnt vmcnt(8)
	s_waitcnt lgkmcnt(0)
	s_barrier
	s_setprio 1
	s_waitcnt lgkmcnt(0)
	v_mfma_f32_16x16x32_bf16 v[60:63], v[154:157], v[192:195], v[60:63]
	v_mfma_f32_16x16x32_bf16 v[56:59], v[162:165], v[192:195], v[56:59]
	v_mfma_f32_16x16x32_bf16 v[44:47], v[154:157], v[200:203], v[44:47]
	v_mfma_f32_16x16x32_bf16 v[40:43], v[162:165], v[200:203], v[40:43]
	v_mfma_f32_16x16x32_bf16 v[28:31], v[154:157], v[208:211], v[28:31]
	v_mfma_f32_16x16x32_bf16 v[24:27], v[162:165], v[208:211], v[24:27]
	v_mfma_f32_16x16x32_bf16 v[12:15], v[154:157], v[216:219], v[12:15]
	v_mfma_f32_16x16x32_bf16 v[8:11], v[162:165], v[216:219], v[8:11]
	v_mfma_f32_16x16x32_bf16 v[60:63], v[158:161], v[196:199], v[60:63]
	v_mfma_f32_16x16x32_bf16 v[56:59], v[172:175], v[196:199], v[56:59]
	v_mfma_f32_16x16x32_bf16 v[44:47], v[158:161], v[204:207], v[44:47]
	v_mfma_f32_16x16x32_bf16 v[40:43], v[172:175], v[204:207], v[40:43]
	v_mfma_f32_16x16x32_bf16 v[28:31], v[158:161], v[212:215], v[28:31]
	v_mfma_f32_16x16x32_bf16 v[24:27], v[172:175], v[212:215], v[24:27]
	v_mfma_f32_16x16x32_bf16 v[12:15], v[158:161], v[220:223], v[12:15]
	v_mfma_f32_16x16x32_bf16 v[8:11], v[172:175], v[220:223], v[8:11]
	s_setprio 0
	s_setprio 1
	v_mfma_f32_16x16x32_bf16 v[52:55], v[176:179], v[192:195], v[52:55]
	v_mfma_f32_16x16x32_bf16 v[48:51], v[184:187], v[192:195], v[48:51]
	v_mfma_f32_16x16x32_bf16 v[36:39], v[176:179], v[200:203], v[36:39]
	v_mfma_f32_16x16x32_bf16 v[32:35], v[184:187], v[200:203], v[32:35]
	v_mfma_f32_16x16x32_bf16 v[20:23], v[176:179], v[208:211], v[20:23]
	v_mfma_f32_16x16x32_bf16 v[16:19], v[184:187], v[208:211], v[16:19]
	v_mfma_f32_16x16x32_bf16 v[4:7], v[176:179], v[216:219], v[4:7]
	v_mfma_f32_16x16x32_bf16 v[0:3], v[184:187], v[216:219], v[0:3]
	v_mfma_f32_16x16x32_bf16 v[52:55], v[180:183], v[196:199], v[52:55]
	v_mfma_f32_16x16x32_bf16 v[48:51], v[188:191], v[196:199], v[48:51]
	v_mfma_f32_16x16x32_bf16 v[36:39], v[180:183], v[204:207], v[36:39]
	v_mfma_f32_16x16x32_bf16 v[32:35], v[188:191], v[204:207], v[32:35]
	v_mfma_f32_16x16x32_bf16 v[20:23], v[180:183], v[212:215], v[20:23]
	v_mfma_f32_16x16x32_bf16 v[16:19], v[188:191], v[212:215], v[16:19]
	v_mfma_f32_16x16x32_bf16 v[4:7], v[180:183], v[220:223], v[4:7]
	v_mfma_f32_16x16x32_bf16 v[0:3], v[188:191], v[220:223], v[0:3]
	s_setprio 0
	s_barrier
	s_add_i32 s56, s56, 2
	s_add_u32 s16, s16, 0x100
	s_addc_u32 s17, s17, 0
	s_add_u32 s49, s49, 0x100
	s_addc_u32 s51, s51, 0
	s_cmp_lt_u32 s56, 62
	s_cbranch_scc1 .LBB0_124
	s_andn2_b64 vcc, exec, s[94:95]
	s_cbranch_vccnz .LBB0_127
	s_barrier

.LBB0_1154:
	ds_read_b128 v[140:143], v157
	ds_read_b128 v[144:147], v157 offset:1024
	s_waitcnt lgkmcnt(0)
	ds_read_b128 v[148:151], v157 offset:2048
	ds_read_b128 v[162:165], v157 offset:3072
	ds_read_b128 v[166:169], v158
	ds_read_b128 v[170:173], v158 offset:1024
	ds_read_b128 v[174:177], v158 offset:2048
	ds_read_b128 v[178:181], v158 offset:3072
	s_add_i32 s72, s46, 2
	s_add_u32 s47, s44, 0xfff00080
	s_addc_u32 s48, s45, -1
	s_cmp_eq_u32 s75, s46
	s_cselect_b32 s46, s43, s76
	s_cselect_b32 s49, s29, s48
	s_cselect_b32 s48, s35, s47
	s_cselect_b32 s47, s31, s77
	s_add_i32 m0, s53, 0xc000
	ds_read_b128 v[182:185], v159
	ds_read_b128 v[186:189], v159 offset:1024
	ds_read_b128 v[190:193], v159 offset:2048
	ds_read_b128 v[194:197], v159 offset:3072
	ds_read_b128 v[198:201], v159 offset:4096
	ds_read_b128 v[202:205], v159 offset:5120
	ds_read_b128 v[206:209], v159 offset:6144
	ds_read_b128 v[210:213], v159 offset:7168
	global_load_lds_dwordx4 v134, s[44:45]
	s_add_i32 m0, s53, 0xe000
	s_nop 0
	global_load_lds_dwordx4 v136, s[44:45]
	s_waitcnt vmcnt(8)
	s_waitcnt lgkmcnt(0)
	s_barrier
	s_setprio 1
	s_waitcnt lgkmcnt(0)
	v_mfma_f32_16x16x32_bf16 v[124:127], v[140:143], v[182:185], v[124:127]
	v_mfma_f32_16x16x32_bf16 v[120:123], v[148:151], v[182:185], v[120:123]
	v_mfma_f32_16x16x32_bf16 v[116:119], v[140:143], v[190:193], v[116:119]
	v_mfma_f32_16x16x32_bf16 v[108:111], v[148:151], v[190:193], v[108:111]
	v_mfma_f32_16x16x32_bf16 v[100:103], v[140:143], v[198:201], v[100:103]
	v_mfma_f32_16x16x32_bf16 v[92:95], v[148:151], v[198:201], v[92:95]
	v_mfma_f32_16x16x32_bf16 v[84:87], v[140:143], v[206:209], v[84:87]
	v_mfma_f32_16x16x32_bf16 v[76:79], v[148:151], v[206:209], v[76:79]
	v_mfma_f32_16x16x32_bf16 v[124:127], v[144:147], v[186:189], v[124:127]
	v_mfma_f32_16x16x32_bf16 v[120:123], v[162:165], v[186:189], v[120:123]
	v_mfma_f32_16x16x32_bf16 v[116:119], v[144:147], v[194:197], v[116:119]
	v_mfma_f32_16x16x32_bf16 v[108:111], v[162:165], v[194:197], v[108:111]
	v_mfma_f32_16x16x32_bf16 v[100:103], v[144:147], v[202:205], v[100:103]
	v_mfma_f32_16x16x32_bf16 v[92:95], v[162:165], v[202:205], v[92:95]
	v_mfma_f32_16x16x32_bf16 v[84:87], v[144:147], v[210:213], v[84:87]
	v_mfma_f32_16x16x32_bf16 v[76:79], v[162:165], v[210:213], v[76:79]
	s_setprio 0
	s_setprio 1
	v_mfma_f32_16x16x32_bf16 v[112:115], v[166:169], v[182:185], v[112:115]
	v_mfma_f32_16x16x32_bf16 v[104:107], v[174:177], v[182:185], v[104:107]
	v_mfma_f32_16x16x32_bf16 v[96:99], v[166:169], v[190:193], v[96:99]
	v_mfma_f32_16x16x32_bf16 v[88:91], v[174:177], v[190:193], v[88:91]
	v_mfma_f32_16x16x32_bf16 v[80:83], v[166:169], v[198:201], v[80:83]
	v_mfma_f32_16x16x32_bf16 v[72:75], v[174:177], v[198:201], v[72:75]
	v_mfma_f32_16x16x32_bf16 v[68:71], v[166:169], v[206:209], v[68:71]
	v_mfma_f32_16x16x32_bf16 v[64:67], v[174:177], v[206:209], v[64:67]
	v_mfma_f32_16x16x32_bf16 v[112:115], v[170:173], v[186:189], v[112:115]
	v_mfma_f32_16x16x32_bf16 v[104:107], v[178:181], v[186:189], v[104:107]
	v_mfma_f32_16x16x32_bf16 v[96:99], v[170:173], v[194:197], v[96:99]
	v_mfma_f32_16x16x32_bf16 v[88:91], v[178:181], v[194:197], v[88:91]
	v_mfma_f32_16x16x32_bf16 v[80:83], v[170:173], v[202:205], v[80:83]
	v_mfma_f32_16x16x32_bf16 v[72:75], v[178:181], v[202:205], v[72:75]
	v_mfma_f32_16x16x32_bf16 v[68:71], v[170:173], v[210:213], v[68:71]
	v_mfma_f32_16x16x32_bf16 v[64:67], v[178:181], v[210:213], v[64:67]
	s_setprio 0
	s_barrier
	s_add_i32 s78, s62, s93
	s_mov_b32 m0, s78
	ds_read_b128 v[182:185], v159 offset:16384
	ds_read_b128 v[186:189], v159 offset:17408
	ds_read_b128 v[190:193], v159 offset:18432
	ds_read_b128 v[194:197], v159 offset:19456
	ds_read_b128 v[198:201], v159 offset:20480
	ds_read_b128 v[202:205], v159 offset:21504
	ds_read_b128 v[206:209], v159 offset:22528
	ds_read_b128 v[210:213], v159 offset:23552
	global_load_lds_dwordx4 v128, s[46:47]
	s_add_i32 m0, s78, 0x2000
	s_add_u32 s78, s46, 0x100000
	v_lshl_add_u64 v[216:217], s[46:47], 0, v[130:131]
	s_addc_u32 s79, s47, 0
	s_add_i32 s80, s63, s93
	global_load_lds_dwordx4 v130, s[46:47]
	s_mov_b32 m0, s80
	v_lshl_add_u64 v[220:221], s[48:49], 0, v[130:131]
	global_load_lds_dwordx4 v128, s[78:79]
	s_add_i32 m0, s80, 0x2000
	s_nop 0
	global_load_lds_dwordx4 v130, s[78:79]
	v_lshl_add_u64 v[218:219], s[48:49], 0, v[128:129]
	s_mov_b32 m0, s53
	s_nop 0
	global_load_lds_dwordx4 v128, s[48:49]
	s_mov_b32 m0, s54
	s_nop 0
	global_load_lds_dwordx4 v130, s[48:49]
	s_waitcnt vmcnt(8)
	s_waitcnt lgkmcnt(0)
	s_barrier
	s_setprio 1
	s_waitcnt lgkmcnt(0)
	v_mfma_f32_16x16x32_bf16 v[60:63], v[140:143], v[182:185], v[60:63]
	v_mfma_f32_16x16x32_bf16 v[56:59], v[148:151], v[182:185], v[56:59]
	v_mfma_f32_16x16x32_bf16 v[52:55], v[140:143], v[190:193], v[52:55]
	v_mfma_f32_16x16x32_bf16 v[40:43], v[148:151], v[190:193], v[40:43]
	v_mfma_f32_16x16x32_bf16 v[36:39], v[140:143], v[198:201], v[36:39]
	v_mfma_f32_16x16x32_bf16 v[24:27], v[148:151], v[198:201], v[24:27]
	v_mfma_f32_16x16x32_bf16 v[20:23], v[140:143], v[206:209], v[20:23]
	v_mfma_f32_16x16x32_bf16 v[8:11], v[148:151], v[206:209], v[8:11]
	v_mfma_f32_16x16x32_bf16 v[60:63], v[144:147], v[186:189], v[60:63]
	v_mfma_f32_16x16x32_bf16 v[56:59], v[162:165], v[186:189], v[56:59]
	v_mfma_f32_16x16x32_bf16 v[52:55], v[144:147], v[194:197], v[52:55]
	v_mfma_f32_16x16x32_bf16 v[40:43], v[162:165], v[194:197], v[40:43]
	v_mfma_f32_16x16x32_bf16 v[36:39], v[144:147], v[202:205], v[36:39]
	v_mfma_f32_16x16x32_bf16 v[24:27], v[162:165], v[202:205], v[24:27]
	v_mfma_f32_16x16x32_bf16 v[20:23], v[144:147], v[210:213], v[20:23]
	v_mfma_f32_16x16x32_bf16 v[8:11], v[162:165], v[210:213], v[8:11]
	s_setprio 0
	s_setprio 1
	v_mfma_f32_16x16x32_bf16 v[48:51], v[166:169], v[182:185], v[48:51]
	v_mfma_f32_16x16x32_bf16 v[44:47], v[174:177], v[182:185], v[44:47]
	v_mfma_f32_16x16x32_bf16 v[32:35], v[166:169], v[190:193], v[32:35]
	v_mfma_f32_16x16x32_bf16 v[28:31], v[174:177], v[190:193], v[28:31]
	v_mfma_f32_16x16x32_bf16 v[16:19], v[166:169], v[198:201], v[16:19]
	v_mfma_f32_16x16x32_bf16 v[12:15], v[174:177], v[198:201], v[12:15]
	v_mfma_f32_16x16x32_bf16 v[4:7], v[166:169], v[206:209], v[4:7]
	v_mfma_f32_16x16x32_bf16 v[0:3], v[174:177], v[206:209], v[0:3]
	v_mfma_f32_16x16x32_bf16 v[48:51], v[170:173], v[186:189], v[48:51]
	v_mfma_f32_16x16x32_bf16 v[44:47], v[178:181], v[186:189], v[44:47]
	v_mfma_f32_16x16x32_bf16 v[32:35], v[170:173], v[194:197], v[32:35]
	v_mfma_f32_16x16x32_bf16 v[28:31], v[178:181], v[194:197], v[28:31]
	v_mfma_f32_16x16x32_bf16 v[16:19], v[170:173], v[202:205], v[16:19]
	v_mfma_f32_16x16x32_bf16 v[12:15], v[178:181], v[202:205], v[12:15]
	v_mfma_f32_16x16x32_bf16 v[4:7], v[170:173], v[210:213], v[4:7]
	v_mfma_f32_16x16x32_bf16 v[0:3], v[178:181], v[210:213], v[0:3]
	s_setprio 0
	s_barrier
	s_add_i32 s78, 0, 0x18000
	v_add_u32_e32 v133, s78, v153
	s_add_i32 s79, 0, 0x1c000
	ds_read_b128 v[140:143], v133
	ds_read_b128 v[144:147], v133 offset:1024
	ds_read_b128 v[148:151], v133 offset:2048
	ds_read_b128 v[162:165], v133 offset:3072
	v_add_u32_e32 v133, s79, v153
	ds_read_b128 v[166:169], v133
	ds_read_b128 v[170:173], v133 offset:1024
	ds_read_b128 v[174:177], v133 offset:2048
	ds_read_b128 v[178:181], v133 offset:3072
	s_add_u32 s48, s48, 0x100000
	s_addc_u32 s49, s49, 0
	s_mov_b32 m0, s55
	ds_read_b128 v[182:185], v159 offset:32768
	ds_read_b128 v[186:189], v159 offset:33792
	ds_read_b128 v[190:193], v159 offset:34816
	ds_read_b128 v[194:197], v159 offset:35840
	ds_read_b128 v[198:201], v159 offset:36864
	ds_read_b128 v[202:205], v159 offset:37888
	ds_read_b128 v[206:209], v159 offset:38912
	ds_read_b128 v[210:213], v159 offset:39936
	global_load_lds_dwordx4 v128, s[48:49]
	s_mov_b32 m0, s56
	s_nop 0
	global_load_lds_dwordx4 v130, s[48:49]
	s_waitcnt vmcnt(8)
	s_waitcnt lgkmcnt(0)
	s_barrier
	s_setprio 1
	s_waitcnt lgkmcnt(0)
	v_mfma_f32_16x16x32_bf16 v[124:127], v[140:143], v[182:185], v[124:127]
	v_mfma_f32_16x16x32_bf16 v[120:123], v[148:151], v[182:185], v[120:123]
	v_mfma_f32_16x16x32_bf16 v[116:119], v[140:143], v[190:193], v[116:119]
	v_mfma_f32_16x16x32_bf16 v[108:111], v[148:151], v[190:193], v[108:111]
	v_mfma_f32_16x16x32_bf16 v[100:103], v[140:143], v[198:201], v[100:103]
	v_mfma_f32_16x16x32_bf16 v[92:95], v[148:151], v[198:201], v[92:95]
	v_mfma_f32_16x16x32_bf16 v[84:87], v[140:143], v[206:209], v[84:87]
	v_mfma_f32_16x16x32_bf16 v[76:79], v[148:151], v[206:209], v[76:79]
	v_mfma_f32_16x16x32_bf16 v[124:127], v[144:147], v[186:189], v[124:127]
	v_mfma_f32_16x16x32_bf16 v[120:123], v[162:165], v[186:189], v[120:123]
	v_mfma_f32_16x16x32_bf16 v[116:119], v[144:147], v[194:197], v[116:119]
	v_mfma_f32_16x16x32_bf16 v[108:111], v[162:165], v[194:197], v[108:111]
	v_mfma_f32_16x16x32_bf16 v[100:103], v[144:147], v[202:205], v[100:103]
	v_mfma_f32_16x16x32_bf16 v[92:95], v[162:165], v[202:205], v[92:95]
	v_mfma_f32_16x16x32_bf16 v[84:87], v[144:147], v[210:213], v[84:87]
	v_mfma_f32_16x16x32_bf16 v[76:79], v[162:165], v[210:213], v[76:79]
	s_setprio 0
	s_setprio 1
	v_mfma_f32_16x16x32_bf16 v[112:115], v[166:169], v[182:185], v[112:115]
	v_mfma_f32_16x16x32_bf16 v[104:107], v[174:177], v[182:185], v[104:107]
	v_mfma_f32_16x16x32_bf16 v[96:99], v[166:169], v[190:193], v[96:99]
	v_mfma_f32_16x16x32_bf16 v[88:91], v[174:177], v[190:193], v[88:91]
	v_mfma_f32_16x16x32_bf16 v[80:83], v[166:169], v[198:201], v[80:83]
	v_mfma_f32_16x16x32_bf16 v[72:75], v[174:177], v[198:201], v[72:75]
	v_mfma_f32_16x16x32_bf16 v[68:71], v[166:169], v[206:209], v[68:71]
	v_mfma_f32_16x16x32_bf16 v[64:67], v[174:177], v[206:209], v[64:67]
	v_mfma_f32_16x16x32_bf16 v[112:115], v[170:173], v[186:189], v[112:115]
	v_mfma_f32_16x16x32_bf16 v[104:107], v[178:181], v[186:189], v[104:107]
	v_mfma_f32_16x16x32_bf16 v[96:99], v[170:173], v[194:197], v[96:99]
	v_mfma_f32_16x16x32_bf16 v[88:91], v[178:181], v[194:197], v[88:91]
	v_mfma_f32_16x16x32_bf16 v[80:83], v[170:173], v[202:205], v[80:83]
	v_mfma_f32_16x16x32_bf16 v[72:75], v[178:181], v[202:205], v[72:75]
	v_mfma_f32_16x16x32_bf16 v[68:71], v[170:173], v[210:213], v[68:71]
	v_mfma_f32_16x16x32_bf16 v[64:67], v[178:181], v[210:213], v[64:67]
	s_setprio 0
	s_barrier
	s_add_i32 s48, s78, s93
	s_add_i32 m0, s48, 0xffffff80
	ds_read_b128 v[182:185], v159 offset:49152
	ds_read_b128 v[186:189], v159 offset:50176
	ds_read_b128 v[190:193], v159 offset:51200
	ds_read_b128 v[194:197], v159 offset:52224
	ds_read_b128 v[198:201], v159 offset:53248
	ds_read_b128 v[202:205], v159 offset:54272
	ds_read_b128 v[206:209], v159 offset:55296
	ds_read_b128 v[210:213], v159 offset:56320
	global_load_lds_dwordx4 v128, s[46:47] offset:128
	s_add_i32 m0, s48, 0x2000
	s_add_u32 s46, s46, 0x100080
	v_lshl_add_u64 v[214:215], v[216:217], 0, s[18:19]
	s_addc_u32 s47, s47, 0
	s_add_i32 s48, s79, s93
	global_load_lds_dwordx4 v[214:215], off
	s_mov_b32 m0, s48
	s_nop 0
	global_load_lds_dwordx4 v128, s[46:47]
	s_add_i32 m0, s48, 0x2000
	s_nop 0
	global_load_lds_dwordx4 v130, s[46:47]
	v_lshl_add_u64 v[214:215], v[218:219], 0, s[18:19]
	s_mov_b32 m0, s60
	s_nop 0
	global_load_lds_dwordx4 v[214:215], off
	v_lshl_add_u64 v[214:215], v[220:221], 0, s[18:19]
	s_mov_b32 m0, s61
	s_nop 0
	global_load_lds_dwordx4 v[214:215], off
	s_waitcnt vmcnt(8)
	s_waitcnt lgkmcnt(0)
	s_barrier
	s_setprio 1
	s_waitcnt lgkmcnt(0)
	v_mfma_f32_16x16x32_bf16 v[60:63], v[140:143], v[182:185], v[60:63]
	v_mfma_f32_16x16x32_bf16 v[56:59], v[148:151], v[182:185], v[56:59]
	v_mfma_f32_16x16x32_bf16 v[52:55], v[140:143], v[190:193], v[52:55]
	v_mfma_f32_16x16x32_bf16 v[40:43], v[148:151], v[190:193], v[40:43]
	v_mfma_f32_16x16x32_bf16 v[36:39], v[140:143], v[198:201], v[36:39]
	v_mfma_f32_16x16x32_bf16 v[24:27], v[148:151], v[198:201], v[24:27]
	v_mfma_f32_16x16x32_bf16 v[20:23], v[140:143], v[206:209], v[20:23]
	v_mfma_f32_16x16x32_bf16 v[8:11], v[148:151], v[206:209], v[8:11]
	v_mfma_f32_16x16x32_bf16 v[60:63], v[144:147], v[186:189], v[60:63]
	v_mfma_f32_16x16x32_bf16 v[56:59], v[162:165], v[186:189], v[56:59]
	v_mfma_f32_16x16x32_bf16 v[52:55], v[144:147], v[194:197], v[52:55]
	v_mfma_f32_16x16x32_bf16 v[40:43], v[162:165], v[194:197], v[40:43]
	v_mfma_f32_16x16x32_bf16 v[36:39], v[144:147], v[202:205], v[36:39]
	v_mfma_f32_16x16x32_bf16 v[24:27], v[162:165], v[202:205], v[24:27]
	v_mfma_f32_16x16x32_bf16 v[20:23], v[144:147], v[210:213], v[20:23]
	v_mfma_f32_16x16x32_bf16 v[8:11], v[162:165], v[210:213], v[8:11]
	s_setprio 0
	s_setprio 1
	v_mfma_f32_16x16x32_bf16 v[48:51], v[166:169], v[182:185], v[48:51]
	v_mfma_f32_16x16x32_bf16 v[44:47], v[174:177], v[182:185], v[44:47]
	v_mfma_f32_16x16x32_bf16 v[32:35], v[166:169], v[190:193], v[32:35]
	v_mfma_f32_16x16x32_bf16 v[28:31], v[174:177], v[190:193], v[28:31]
	v_mfma_f32_16x16x32_bf16 v[16:19], v[166:169], v[198:201], v[16:19]
	v_mfma_f32_16x16x32_bf16 v[12:15], v[174:177], v[198:201], v[12:15]
	v_mfma_f32_16x16x32_bf16 v[4:7], v[166:169], v[206:209], v[4:7]
	v_mfma_f32_16x16x32_bf16 v[0:3], v[174:177], v[206:209], v[0:3]
	v_mfma_f32_16x16x32_bf16 v[48:51], v[170:173], v[186:189], v[48:51]
	v_mfma_f32_16x16x32_bf16 v[44:47], v[178:181], v[186:189], v[44:47]
	v_mfma_f32_16x16x32_bf16 v[32:35], v[170:173], v[194:197], v[32:35]
	v_mfma_f32_16x16x32_bf16 v[28:31], v[178:181], v[194:197], v[28:31]
	v_mfma_f32_16x16x32_bf16 v[16:19], v[170:173], v[202:205], v[16:19]
	v_mfma_f32_16x16x32_bf16 v[12:15], v[178:181], v[202:205], v[12:15]
	v_mfma_f32_16x16x32_bf16 v[4:7], v[170:173], v[210:213], v[4:7]
	v_mfma_f32_16x16x32_bf16 v[0:3], v[178:181], v[210:213], v[0:3]
	s_setprio 0
	s_barrier
	s_add_u32 s44, s44, 0x100
	s_addc_u32 s45, s45, 0
	s_add_u32 s76, s76, 0x100
	s_addc_u32 s77, s77, 0
	s_cmp_lt_i32 s72, s27
	s_mov_b32 s46, s72
	s_cbranch_scc1 .LBB0_1154
	s_andn2_b64 vcc, exec, s[94:95]
	s_cbranch_vccnz .LBB0_1157
	s_barrier

.LBB0_1297:
	v_add_u32_e32 v154, s80, v181
	v_add_u32_e32 v170, s81, v181
	ds_read_b128 v[142:145], v154
	ds_read_b128 v[146:149], v154 offset:1024
	ds_read_b128 v[150:153], v154 offset:2048
	ds_read_b128 v[154:157], v154 offset:3072
	ds_read_b128 v[158:161], v170
	ds_read_b128 v[162:165], v170 offset:1024
	ds_read_b128 v[166:169], v170 offset:2048
	ds_read_b128 v[170:173], v170 offset:3072
	s_add_i32 s72, s62, 2
	s_add_u32 s24, s60, 0xfff80080
	s_addc_u32 s25, s61, -1
	s_cmp_eq_u32 s97, s62
	s_cselect_b32 s62, s96, vcc_lo
	s_cselect_b32 s65, s41, s25
	s_cselect_b32 s64, s45, s24
	s_cselect_b32 s63, s43, vcc_hi
	s_add_i32 m0, s55, 0xc000
	ds_read_b128 v[174:177], v183
	ds_read_b128 v[184:187], v183 offset:1024
	ds_read_b128 v[188:191], v183 offset:2048
	ds_read_b128 v[192:195], v183 offset:3072
	ds_read_b128 v[196:199], v183 offset:4096
	ds_read_b128 v[200:203], v183 offset:5120
	ds_read_b128 v[204:207], v183 offset:6144
	ds_read_b128 v[208:211], v183 offset:7168
	global_load_lds_dwordx4 v138, s[60:61]
	s_add_i32 m0, s55, 0xe000
	s_nop 0
	global_load_lds_dwordx4 v140, s[60:61]
	s_waitcnt vmcnt(8)
	s_waitcnt lgkmcnt(0)
	s_barrier
	s_setprio 1
	s_waitcnt lgkmcnt(0)
	v_mfma_i32_16x16x64_i8 v[124:127], v[142:145], v[174:177], v[124:127]
	v_mfma_i32_16x16x64_i8 v[120:123], v[150:153], v[174:177], v[120:123]
	v_mfma_i32_16x16x64_i8 v[116:119], v[142:145], v[188:191], v[116:119]
	v_mfma_i32_16x16x64_i8 v[112:115], v[150:153], v[188:191], v[112:115]
	v_mfma_i32_16x16x64_i8 v[104:107], v[142:145], v[196:199], v[104:107]
	v_mfma_i32_16x16x64_i8 v[96:99], v[150:153], v[196:199], v[96:99]
	v_mfma_i32_16x16x64_i8 v[88:91], v[142:145], v[204:207], v[88:91]
	v_mfma_i32_16x16x64_i8 v[80:83], v[150:153], v[204:207], v[80:83]
	v_mfma_i32_16x16x64_i8 v[124:127], v[146:149], v[184:187], v[124:127]
	v_mfma_i32_16x16x64_i8 v[120:123], v[154:157], v[184:187], v[120:123]
	v_mfma_i32_16x16x64_i8 v[116:119], v[146:149], v[192:195], v[116:119]
	v_mfma_i32_16x16x64_i8 v[112:115], v[154:157], v[192:195], v[112:115]
	v_mfma_i32_16x16x64_i8 v[104:107], v[146:149], v[200:203], v[104:107]
	v_mfma_i32_16x16x64_i8 v[96:99], v[154:157], v[200:203], v[96:99]
	v_mfma_i32_16x16x64_i8 v[88:91], v[146:149], v[208:211], v[88:91]
	v_mfma_i32_16x16x64_i8 v[80:83], v[154:157], v[208:211], v[80:83]
	s_setprio 0
	s_setprio 1
	v_mfma_i32_16x16x64_i8 v[108:111], v[158:161], v[174:177], v[108:111]
	v_mfma_i32_16x16x64_i8 v[100:103], v[166:169], v[174:177], v[100:103]
	v_mfma_i32_16x16x64_i8 v[92:95], v[158:161], v[188:191], v[92:95]
	v_mfma_i32_16x16x64_i8 v[84:87], v[166:169], v[188:191], v[84:87]
	v_mfma_i32_16x16x64_i8 v[76:79], v[158:161], v[196:199], v[76:79]
	v_mfma_i32_16x16x64_i8 v[72:75], v[166:169], v[196:199], v[72:75]
	v_mfma_i32_16x16x64_i8 v[68:71], v[158:161], v[204:207], v[68:71]
	v_mfma_i32_16x16x64_i8 v[64:67], v[166:169], v[204:207], v[64:67]
	v_mfma_i32_16x16x64_i8 v[108:111], v[162:165], v[184:187], v[108:111]
	v_mfma_i32_16x16x64_i8 v[100:103], v[170:173], v[184:187], v[100:103]
	v_mfma_i32_16x16x64_i8 v[92:95], v[162:165], v[192:195], v[92:95]
	v_mfma_i32_16x16x64_i8 v[84:87], v[170:173], v[192:195], v[84:87]
	v_mfma_i32_16x16x64_i8 v[76:79], v[162:165], v[200:203], v[76:79]
	v_mfma_i32_16x16x64_i8 v[72:75], v[170:173], v[200:203], v[72:75]
	v_mfma_i32_16x16x64_i8 v[68:71], v[162:165], v[208:211], v[68:71]
	v_mfma_i32_16x16x64_i8 v[64:67], v[170:173], v[208:211], v[64:67]
	s_setprio 0
	s_barrier
	s_add_i32 s24, s80, s93
	s_mov_b32 m0, s24
	ds_read_b128 v[174:177], v183 offset:16384
	ds_read_b128 v[184:187], v183 offset:17408
	ds_read_b128 v[188:191], v183 offset:18432
	ds_read_b128 v[192:195], v183 offset:19456
	ds_read_b128 v[196:199], v183 offset:20480
	ds_read_b128 v[200:203], v183 offset:21504
	ds_read_b128 v[204:207], v183 offset:22528
	ds_read_b128 v[208:211], v183 offset:23552
	global_load_lds_dwordx4 v130, s[62:63]
	s_add_i32 m0, s24, 0x2000
	s_add_u32 s24, s62, 0x80000
	v_lshl_add_u64 v[212:213], s[62:63], 0, v[134:135]
	s_addc_u32 s25, s63, 0
	s_add_i32 s73, s81, s93
	global_load_lds_dwordx4 v134, s[62:63]
	s_mov_b32 m0, s73
	s_nop 0
	global_load_lds_dwordx4 v130, s[24:25]
	s_add_i32 m0, s73, 0x2000
	s_nop 0
	global_load_lds_dwordx4 v134, s[24:25]
	s_mov_b32 m0, s55
	s_nop 0
	global_load_lds_dwordx4 v128, s[64:65]
	s_mov_b32 m0, s57
	s_nop 0
	global_load_lds_dwordx4 v132, s[64:65]
	s_waitcnt vmcnt(8)
	s_waitcnt lgkmcnt(0)
	s_barrier
	s_setprio 1
	s_waitcnt lgkmcnt(0)
	v_mfma_i32_16x16x64_i8 v[60:63], v[142:145], v[174:177], v[60:63]
	v_mfma_i32_16x16x64_i8 v[56:59], v[150:153], v[174:177], v[56:59]
	v_mfma_i32_16x16x64_i8 v[52:55], v[142:145], v[188:191], v[52:55]
	v_mfma_i32_16x16x64_i8 v[48:51], v[150:153], v[188:191], v[48:51]
	v_mfma_i32_16x16x64_i8 v[44:47], v[142:145], v[196:199], v[44:47]
	v_mfma_i32_16x16x64_i8 v[40:43], v[150:153], v[196:199], v[40:43]
	v_mfma_i32_16x16x64_i8 v[36:39], v[142:145], v[204:207], v[36:39]
	v_mfma_i32_16x16x64_i8 v[32:35], v[150:153], v[204:207], v[32:35]
	v_mfma_i32_16x16x64_i8 v[60:63], v[146:149], v[184:187], v[60:63]
	v_mfma_i32_16x16x64_i8 v[56:59], v[154:157], v[184:187], v[56:59]
	v_mfma_i32_16x16x64_i8 v[52:55], v[146:149], v[192:195], v[52:55]
	v_mfma_i32_16x16x64_i8 v[48:51], v[154:157], v[192:195], v[48:51]
	v_mfma_i32_16x16x64_i8 v[44:47], v[146:149], v[200:203], v[44:47]
	v_mfma_i32_16x16x64_i8 v[40:43], v[154:157], v[200:203], v[40:43]
	v_mfma_i32_16x16x64_i8 v[36:39], v[146:149], v[208:211], v[36:39]
	v_mfma_i32_16x16x64_i8 v[32:35], v[154:157], v[208:211], v[32:35]
	s_setprio 0
	s_setprio 1
	v_mfma_i32_16x16x64_i8 v[28:31], v[158:161], v[174:177], v[28:31]
	v_mfma_i32_16x16x64_i8 v[24:27], v[166:169], v[174:177], v[24:27]
	v_mfma_i32_16x16x64_i8 v[20:23], v[158:161], v[188:191], v[20:23]
	v_mfma_i32_16x16x64_i8 v[16:19], v[166:169], v[188:191], v[16:19]
	v_mfma_i32_16x16x64_i8 v[12:15], v[158:161], v[196:199], v[12:15]
	v_mfma_i32_16x16x64_i8 v[8:11], v[166:169], v[196:199], v[8:11]
	v_mfma_i32_16x16x64_i8 v[4:7], v[158:161], v[204:207], v[4:7]
	v_mfma_i32_16x16x64_i8 v[0:3], v[166:169], v[204:207], v[0:3]
	v_mfma_i32_16x16x64_i8 v[28:31], v[162:165], v[184:187], v[28:31]
	v_mfma_i32_16x16x64_i8 v[24:27], v[170:173], v[184:187], v[24:27]
	v_mfma_i32_16x16x64_i8 v[20:23], v[162:165], v[192:195], v[20:23]
	v_mfma_i32_16x16x64_i8 v[16:19], v[170:173], v[192:195], v[16:19]
	v_mfma_i32_16x16x64_i8 v[12:15], v[162:165], v[200:203], v[12:15]
	v_mfma_i32_16x16x64_i8 v[8:11], v[170:173], v[200:203], v[8:11]
	v_mfma_i32_16x16x64_i8 v[4:7], v[162:165], v[208:211], v[4:7]
	v_mfma_i32_16x16x64_i8 v[0:3], v[170:173], v[208:211], v[0:3]
	s_setprio 0
	s_barrier
	s_add_i32 s73, 0, 0x18000
	s_add_i32 s66, 0, 0x1c000
	v_add_u32_e32 v154, s73, v181
	v_add_u32_e32 v170, s66, v181
	ds_read_b128 v[142:145], v154
	ds_read_b128 v[146:149], v154 offset:1024
	ds_read_b128 v[150:153], v154 offset:2048
	ds_read_b128 v[154:157], v154 offset:3072
	ds_read_b128 v[158:161], v170
	ds_read_b128 v[162:165], v170 offset:1024
	ds_read_b128 v[166:169], v170 offset:2048
	ds_read_b128 v[170:173], v170 offset:3072
	s_add_u32 s24, s64, 0x80000
	s_addc_u32 s25, s65, 0
	s_mov_b32 m0, s69
	ds_read_b128 v[174:177], v183 offset:32768
	ds_read_b128 v[184:187], v183 offset:33792
	ds_read_b128 v[188:191], v183 offset:34816
	ds_read_b128 v[192:195], v183 offset:35840
	ds_read_b128 v[196:199], v183 offset:36864
	ds_read_b128 v[200:203], v183 offset:37888
	ds_read_b128 v[204:207], v183 offset:38912
	ds_read_b128 v[208:211], v183 offset:39936
	global_load_lds_dwordx4 v128, s[24:25]
	s_mov_b32 m0, s74
	s_nop 0
	global_load_lds_dwordx4 v132, s[24:25]
	s_waitcnt vmcnt(8)
	s_waitcnt lgkmcnt(0)
	s_barrier
	s_setprio 1
	s_waitcnt lgkmcnt(0)
	v_mfma_i32_16x16x64_i8 v[124:127], v[142:145], v[174:177], v[124:127]
	v_mfma_i32_16x16x64_i8 v[120:123], v[150:153], v[174:177], v[120:123]
	v_mfma_i32_16x16x64_i8 v[116:119], v[142:145], v[188:191], v[116:119]
	v_mfma_i32_16x16x64_i8 v[112:115], v[150:153], v[188:191], v[112:115]
	v_mfma_i32_16x16x64_i8 v[104:107], v[142:145], v[196:199], v[104:107]
	v_mfma_i32_16x16x64_i8 v[96:99], v[150:153], v[196:199], v[96:99]
	v_mfma_i32_16x16x64_i8 v[88:91], v[142:145], v[204:207], v[88:91]
	v_mfma_i32_16x16x64_i8 v[80:83], v[150:153], v[204:207], v[80:83]
	v_mfma_i32_16x16x64_i8 v[124:127], v[146:149], v[184:187], v[124:127]
	v_mfma_i32_16x16x64_i8 v[120:123], v[154:157], v[184:187], v[120:123]
	v_mfma_i32_16x16x64_i8 v[116:119], v[146:149], v[192:195], v[116:119]
	v_mfma_i32_16x16x64_i8 v[112:115], v[154:157], v[192:195], v[112:115]
	v_mfma_i32_16x16x64_i8 v[104:107], v[146:149], v[200:203], v[104:107]
	v_mfma_i32_16x16x64_i8 v[96:99], v[154:157], v[200:203], v[96:99]
	v_mfma_i32_16x16x64_i8 v[88:91], v[146:149], v[208:211], v[88:91]
	v_mfma_i32_16x16x64_i8 v[80:83], v[154:157], v[208:211], v[80:83]
	s_setprio 0
	s_setprio 1
	v_mfma_i32_16x16x64_i8 v[108:111], v[158:161], v[174:177], v[108:111]
	v_mfma_i32_16x16x64_i8 v[100:103], v[166:169], v[174:177], v[100:103]
	v_mfma_i32_16x16x64_i8 v[92:95], v[158:161], v[188:191], v[92:95]
	v_mfma_i32_16x16x64_i8 v[84:87], v[166:169], v[188:191], v[84:87]
	v_mfma_i32_16x16x64_i8 v[76:79], v[158:161], v[196:199], v[76:79]
	v_mfma_i32_16x16x64_i8 v[72:75], v[166:169], v[196:199], v[72:75]
	v_mfma_i32_16x16x64_i8 v[68:71], v[158:161], v[204:207], v[68:71]
	v_mfma_i32_16x16x64_i8 v[64:67], v[166:169], v[204:207], v[64:67]
	v_mfma_i32_16x16x64_i8 v[108:111], v[162:165], v[184:187], v[108:111]
	v_mfma_i32_16x16x64_i8 v[100:103], v[170:173], v[184:187], v[100:103]
	v_mfma_i32_16x16x64_i8 v[92:95], v[162:165], v[192:195], v[92:95]
	v_mfma_i32_16x16x64_i8 v[84:87], v[170:173], v[192:195], v[84:87]
	v_mfma_i32_16x16x64_i8 v[76:79], v[162:165], v[200:203], v[76:79]
	v_mfma_i32_16x16x64_i8 v[72:75], v[170:173], v[200:203], v[72:75]
	v_mfma_i32_16x16x64_i8 v[68:71], v[162:165], v[208:211], v[68:71]
	v_mfma_i32_16x16x64_i8 v[64:67], v[170:173], v[208:211], v[64:67]
	s_setprio 0
	s_barrier
	s_add_i32 s24, s73, s93
	s_add_i32 m0, s24, 0xffffff80
	ds_read_b128 v[174:177], v183 offset:49152
	ds_read_b128 v[184:187], v183 offset:50176
	ds_read_b128 v[188:191], v183 offset:51200
	ds_read_b128 v[192:195], v183 offset:52224
	ds_read_b128 v[196:199], v183 offset:53248
	ds_read_b128 v[200:203], v183 offset:54272
	ds_read_b128 v[204:207], v183 offset:55296
	ds_read_b128 v[208:211], v183 offset:56320
	global_load_lds_dwordx4 v130, s[62:63] offset:128
	s_add_i32 m0, s24, 0x2000
	s_add_u32 s24, s62, 0x80080
	v_lshl_add_u64 v[178:179], v[212:213], 0, s[38:39]
	s_addc_u32 s25, s63, 0
	s_add_i32 s62, s66, s93
	global_load_lds_dwordx4 v[178:179], off
	s_mov_b32 m0, s62
	s_nop 0
	global_load_lds_dwordx4 v130, s[24:25]
	s_add_i32 m0, s62, 0x2000
	s_nop 0
	global_load_lds_dwordx4 v134, s[24:25]
	s_add_i32 m0, s77, 0xffffff80
	s_nop 0
	global_load_lds_dwordx4 v128, s[64:65] offset:128
	s_add_i32 m0, s78, 0xffffff80
	s_nop 0
	global_load_lds_dwordx4 v132, s[64:65] offset:128
	s_waitcnt vmcnt(8)
	s_waitcnt lgkmcnt(0)
	s_barrier
	s_setprio 1
	s_waitcnt lgkmcnt(0)
	v_mfma_i32_16x16x64_i8 v[60:63], v[142:145], v[174:177], v[60:63]
	v_mfma_i32_16x16x64_i8 v[56:59], v[150:153], v[174:177], v[56:59]
	v_mfma_i32_16x16x64_i8 v[52:55], v[142:145], v[188:191], v[52:55]
	v_mfma_i32_16x16x64_i8 v[48:51], v[150:153], v[188:191], v[48:51]
	v_mfma_i32_16x16x64_i8 v[44:47], v[142:145], v[196:199], v[44:47]
	v_mfma_i32_16x16x64_i8 v[40:43], v[150:153], v[196:199], v[40:43]
	v_mfma_i32_16x16x64_i8 v[36:39], v[142:145], v[204:207], v[36:39]
	v_mfma_i32_16x16x64_i8 v[32:35], v[150:153], v[204:207], v[32:35]
	v_mfma_i32_16x16x64_i8 v[60:63], v[146:149], v[184:187], v[60:63]
	v_mfma_i32_16x16x64_i8 v[56:59], v[154:157], v[184:187], v[56:59]
	v_mfma_i32_16x16x64_i8 v[52:55], v[146:149], v[192:195], v[52:55]
	v_mfma_i32_16x16x64_i8 v[48:51], v[154:157], v[192:195], v[48:51]
	v_mfma_i32_16x16x64_i8 v[44:47], v[146:149], v[200:203], v[44:47]
	v_mfma_i32_16x16x64_i8 v[40:43], v[154:157], v[200:203], v[40:43]
	v_mfma_i32_16x16x64_i8 v[36:39], v[146:149], v[208:211], v[36:39]
	v_mfma_i32_16x16x64_i8 v[32:35], v[154:157], v[208:211], v[32:35]
	s_setprio 0
	s_setprio 1
	v_mfma_i32_16x16x64_i8 v[28:31], v[158:161], v[174:177], v[28:31]
	v_mfma_i32_16x16x64_i8 v[24:27], v[166:169], v[174:177], v[24:27]
	v_mfma_i32_16x16x64_i8 v[20:23], v[158:161], v[188:191], v[20:23]
	v_mfma_i32_16x16x64_i8 v[16:19], v[166:169], v[188:191], v[16:19]
	v_mfma_i32_16x16x64_i8 v[12:15], v[158:161], v[196:199], v[12:15]
	v_mfma_i32_16x16x64_i8 v[8:11], v[166:169], v[196:199], v[8:11]
	v_mfma_i32_16x16x64_i8 v[4:7], v[158:161], v[204:207], v[4:7]
	v_mfma_i32_16x16x64_i8 v[0:3], v[166:169], v[204:207], v[0:3]
	v_mfma_i32_16x16x64_i8 v[28:31], v[162:165], v[184:187], v[28:31]
	v_mfma_i32_16x16x64_i8 v[24:27], v[170:173], v[184:187], v[24:27]
	v_mfma_i32_16x16x64_i8 v[20:23], v[162:165], v[192:195], v[20:23]
	v_mfma_i32_16x16x64_i8 v[16:19], v[170:173], v[192:195], v[16:19]
	v_mfma_i32_16x16x64_i8 v[12:15], v[162:165], v[200:203], v[12:15]
	v_mfma_i32_16x16x64_i8 v[8:11], v[170:173], v[200:203], v[8:11]
	v_mfma_i32_16x16x64_i8 v[4:7], v[162:165], v[208:211], v[4:7]
	v_mfma_i32_16x16x64_i8 v[0:3], v[170:173], v[208:211], v[0:3]
	s_setprio 0
	s_barrier
	s_add_u32 s60, s60, 0x100
	s_addc_u32 s61, s61, 0
	s_add_u32 vcc_lo, vcc_lo, 0x100
	s_addc_u32 vcc_hi, vcc_hi, 0
	s_cmp_ge_i32 s72, s91
	s_mov_b32 s62, s72
	s_cbranch_scc0 .LBB0_1297
	s_andn2_b64 vcc, exec, s[58:59]
	s_cbranch_vccnz .LBB0_1311
	global_load_dword v142, v131, s[10:11] sc1
	s_waitcnt vmcnt(0)
	v_cmp_lt_u32_e32 vcc, s7, v142
	s_cbranch_vccnz .LBB0_1310
	s_mov_b32 s41, 0x3ffff8
	s_branch .LBB0_1302

.LBB0_1444:
	ds_read_b128 v[24:27], v191
	ds_read_b128 v[28:31], v191 offset:1024
	ds_read_b128 v[16:19], v191 offset:2048
	ds_read_b128 v[20:23], v191 offset:3072
	ds_read_b128 v[8:11], v192
	ds_read_b128 v[12:15], v192 offset:1024
	s_waitcnt lgkmcnt(0)
	ds_read_b128 v[0:3], v192 offset:2048
	ds_read_b128 v[4:7], v192 offset:3072
	s_add_i32 vcc_hi, s62, 2
	s_add_u32 s60, s58, 0x100
	s_addc_u32 s61, s59, 0
	s_cmp_eq_u32 s53, s62
	s_cselect_b32 s62, s56, s97
	s_cselect_b32 s65, s55, s61
	s_cselect_b32 s64, s54, s60
	s_cselect_b32 s63, s57, vcc_lo
	s_add_i32 m0, s31, 0xc000
	ds_read_b128 v[172:175], v193
	ds_read_b128 v[176:179], v193 offset:1024
	ds_read_b128 v[194:197], v193 offset:2048
	ds_read_b128 v[198:201], v193 offset:3072
	ds_read_b128 v[202:205], v193 offset:4096
	ds_read_b128 v[206:209], v193 offset:5120
	ds_read_b128 v[210:213], v193 offset:6144
	ds_read_b128 v[214:217], v193 offset:7168
	global_load_lds_dwordx4 v166, s[58:59]
	s_add_i32 m0, s31, 0xe000
	s_nop 0
	global_load_lds_dwordx4 v168, s[58:59]
	s_waitcnt vmcnt(8)
	s_waitcnt lgkmcnt(0)
	s_barrier
	s_setprio 1
	s_waitcnt lgkmcnt(0)
	v_mfma_f32_16x16x128_f8f6f4 v[156:159], v[24:31], v[172:179], v[156:159]
	v_mfma_f32_16x16x128_f8f6f4 v[152:155], v[16:23], v[172:179], v[152:155]
	v_mfma_f32_16x16x128_f8f6f4 v[148:151], v[24:31], v[194:201], v[148:151]
	v_mfma_f32_16x16x128_f8f6f4 v[140:143], v[16:23], v[194:201], v[140:143]
	v_mfma_f32_16x16x128_f8f6f4 v[132:135], v[24:31], v[202:209], v[132:135]
	v_mfma_f32_16x16x128_f8f6f4 v[124:127], v[16:23], v[202:209], v[124:127]
	v_mfma_f32_16x16x128_f8f6f4 v[116:119], v[24:31], v[210:217], v[116:119]
	v_mfma_f32_16x16x128_f8f6f4 v[108:111], v[16:23], v[210:217], v[108:111]
	s_setprio 0
	s_setprio 1
	v_mfma_f32_16x16x128_f8f6f4 v[144:147], v[8:15], v[172:179], v[144:147]
	v_mfma_f32_16x16x128_f8f6f4 v[136:139], v[0:7], v[172:179], v[136:139]
	v_mfma_f32_16x16x128_f8f6f4 v[128:131], v[8:15], v[194:201], v[128:131]
	v_mfma_f32_16x16x128_f8f6f4 v[120:123], v[0:7], v[194:201], v[120:123]
	v_mfma_f32_16x16x128_f8f6f4 v[112:115], v[8:15], v[202:209], v[112:115]
	v_mfma_f32_16x16x128_f8f6f4 v[104:107], v[0:7], v[202:209], v[104:107]
	v_mfma_f32_16x16x128_f8f6f4 v[100:103], v[8:15], v[210:217], v[100:103]
	v_mfma_f32_16x16x128_f8f6f4 v[96:99], v[0:7], v[210:217], v[96:99]
	s_setprio 0
	s_barrier
	s_add_i32 s24, s82, s93
	s_mov_b32 m0, s24
	ds_read_b128 v[194:197], v193 offset:16384
	ds_read_b128 v[198:201], v193 offset:17408
	ds_read_b128 v[202:205], v193 offset:18432
	ds_read_b128 v[206:209], v193 offset:19456
	ds_read_b128 v[210:213], v193 offset:20480
	ds_read_b128 v[214:217], v193 offset:21504
	ds_read_b128 v[218:221], v193 offset:22528
	ds_read_b128 v[222:225], v193 offset:23552
	global_load_lds_dwordx4 v160, s[62:63]
	s_add_i32 m0, s24, 0x2000
	s_add_u32 s24, s62, 0x158000
	s_addc_u32 s25, s63, 0
	s_add_i32 s58, s83, s93
	global_load_lds_dwordx4 v162, s[62:63]
	s_mov_b32 m0, s58
	s_nop 0
	global_load_lds_dwordx4 v160, s[24:25]
	s_add_i32 m0, s58, 0x2000
	s_nop 0
	global_load_lds_dwordx4 v162, s[24:25]
	s_mov_b32 m0, s31
	s_nop 0
	global_load_lds_dwordx4 v160, s[64:65]
	s_mov_b32 m0, s47
	s_nop 0
	global_load_lds_dwordx4 v162, s[64:65]
	s_waitcnt vmcnt(8)
	s_waitcnt lgkmcnt(0)
	s_barrier
	s_setprio 1
	s_waitcnt lgkmcnt(0)
	v_mfma_f32_16x16x128_f8f6f4 v[92:95], v[24:31], v[194:201], v[92:95]
	v_mfma_f32_16x16x128_f8f6f4 v[88:91], v[16:23], v[194:201], v[88:91]
	v_mfma_f32_16x16x128_f8f6f4 v[84:87], v[24:31], v[202:209], v[84:87]
	v_mfma_f32_16x16x128_f8f6f4 v[72:75], v[16:23], v[202:209], v[72:75]
	v_mfma_f32_16x16x128_f8f6f4 v[68:71], v[24:31], v[210:217], v[68:71]
	v_mfma_f32_16x16x128_f8f6f4 v[56:59], v[16:23], v[210:217], v[56:59]
	v_mfma_f32_16x16x128_f8f6f4 v[52:55], v[24:31], v[218:225], v[52:55]
	v_mfma_f32_16x16x128_f8f6f4 v[40:43], v[16:23], v[218:225], v[40:43]
	s_setprio 0
	s_setprio 1
	v_mfma_f32_16x16x128_f8f6f4 v[80:83], v[8:15], v[194:201], v[80:83]
	v_mfma_f32_16x16x128_f8f6f4 v[76:79], v[0:7], v[194:201], v[76:79]
	v_mfma_f32_16x16x128_f8f6f4 v[64:67], v[8:15], v[202:209], v[64:67]
	v_mfma_f32_16x16x128_f8f6f4 v[60:63], v[0:7], v[202:209], v[60:63]
	v_mfma_f32_16x16x128_f8f6f4 v[48:51], v[8:15], v[210:217], v[48:51]
	v_mfma_f32_16x16x128_f8f6f4 v[44:47], v[0:7], v[210:217], v[44:47]
	v_mfma_f32_16x16x128_f8f6f4 v[36:39], v[8:15], v[218:225], v[36:39]
	v_mfma_f32_16x16x128_f8f6f4 v[32:35], v[0:7], v[218:225], v[32:35]
	s_setprio 0
	s_barrier
	s_add_i32 s58, 0, 0x18000
	s_add_i32 s59, 0, 0x1c000
	v_add_u32_e32 v12, s58, v187
	v_add_u32_e32 v28, s59, v187
	ds_read_b128 v[0:3], v12
	ds_read_b128 v[4:7], v12 offset:1024
	ds_read_b128 v[8:11], v12 offset:2048
	ds_read_b128 v[12:15], v12 offset:3072
	ds_read_b128 v[16:19], v28
	ds_read_b128 v[20:23], v28 offset:1024
	ds_read_b128 v[24:27], v28 offset:2048
	ds_read_b128 v[28:31], v28 offset:3072
	s_add_u32 s24, s64, 0x158000
	s_addc_u32 s25, s65, 0
	s_mov_b32 m0, s49
	ds_read_b128 v[194:197], v193 offset:32768
	ds_read_b128 v[198:201], v193 offset:33792
	ds_read_b128 v[202:205], v193 offset:34816
	ds_read_b128 v[206:209], v193 offset:35840
	ds_read_b128 v[210:213], v193 offset:36864
	ds_read_b128 v[214:217], v193 offset:37888
	ds_read_b128 v[218:221], v193 offset:38912
	ds_read_b128 v[222:225], v193 offset:39936
	global_load_lds_dwordx4 v160, s[24:25]
	s_mov_b32 m0, s69
	s_nop 0
	global_load_lds_dwordx4 v162, s[24:25]
	s_waitcnt vmcnt(8)
	s_waitcnt lgkmcnt(0)
	s_barrier
	s_setprio 1
	s_waitcnt lgkmcnt(0)
	v_mfma_f32_16x16x128_f8f6f4 v[156:159], v[0:7], v[194:201], v[156:159]
	v_mfma_f32_16x16x128_f8f6f4 v[152:155], v[8:15], v[194:201], v[152:155]
	v_mfma_f32_16x16x128_f8f6f4 v[148:151], v[0:7], v[202:209], v[148:151]
	v_mfma_f32_16x16x128_f8f6f4 v[140:143], v[8:15], v[202:209], v[140:143]
	v_mfma_f32_16x16x128_f8f6f4 v[132:135], v[0:7], v[210:217], v[132:135]
	v_mfma_f32_16x16x128_f8f6f4 v[124:127], v[8:15], v[210:217], v[124:127]
	v_mfma_f32_16x16x128_f8f6f4 v[116:119], v[0:7], v[218:225], v[116:119]
	v_mfma_f32_16x16x128_f8f6f4 v[108:111], v[8:15], v[218:225], v[108:111]
	s_setprio 0
	s_setprio 1
	v_mfma_f32_16x16x128_f8f6f4 v[144:147], v[16:23], v[194:201], v[144:147]
	v_mfma_f32_16x16x128_f8f6f4 v[136:139], v[24:31], v[194:201], v[136:139]
	v_mfma_f32_16x16x128_f8f6f4 v[128:131], v[16:23], v[202:209], v[128:131]
	v_mfma_f32_16x16x128_f8f6f4 v[120:123], v[24:31], v[202:209], v[120:123]
	v_mfma_f32_16x16x128_f8f6f4 v[112:115], v[16:23], v[210:217], v[112:115]
	v_mfma_f32_16x16x128_f8f6f4 v[104:107], v[24:31], v[210:217], v[104:107]
	v_mfma_f32_16x16x128_f8f6f4 v[100:103], v[16:23], v[218:225], v[100:103]
	v_mfma_f32_16x16x128_f8f6f4 v[96:99], v[24:31], v[218:225], v[96:99]
	s_setprio 0
	s_barrier
	s_add_i32 s24, s58, s93
	s_add_i32 m0, s24, 0xffffff80
	ds_read_b128 v[194:197], v193 offset:49152
	ds_read_b128 v[198:201], v193 offset:50176
	ds_read_b128 v[202:205], v193 offset:51200
	ds_read_b128 v[206:209], v193 offset:52224
	ds_read_b128 v[210:213], v193 offset:53248
	ds_read_b128 v[214:217], v193 offset:54272
	ds_read_b128 v[218:221], v193 offset:55296
	ds_read_b128 v[222:225], v193 offset:56320
	global_load_lds_dwordx4 v160, s[62:63] offset:128
	s_add_i32 m0, s24, 0x1f80
	s_add_u32 s24, s62, 0x158080
	s_addc_u32 s25, s63, 0
	s_add_i32 s58, s59, s93
	global_load_lds_dwordx4 v162, s[62:63] offset:128
	s_mov_b32 m0, s58
	s_nop 0
	global_load_lds_dwordx4 v160, s[24:25]
	s_add_i32 m0, s58, 0x2000
	s_nop 0
	global_load_lds_dwordx4 v162, s[24:25]
	s_add_i32 m0, s79, 0xffffff80
	s_nop 0
	global_load_lds_dwordx4 v160, s[64:65] offset:128
	s_add_i32 m0, s80, 0xffffff80
	s_nop 0
	global_load_lds_dwordx4 v162, s[64:65] offset:128
	s_waitcnt vmcnt(8)
	s_waitcnt lgkmcnt(0)
	s_barrier
	s_setprio 1
	s_waitcnt lgkmcnt(0)
	v_mfma_f32_16x16x128_f8f6f4 v[92:95], v[0:7], v[194:201], v[92:95]
	v_mfma_f32_16x16x128_f8f6f4 v[88:91], v[8:15], v[194:201], v[88:91]
	v_mfma_f32_16x16x128_f8f6f4 v[84:87], v[0:7], v[202:209], v[84:87]
	v_mfma_f32_16x16x128_f8f6f4 v[72:75], v[8:15], v[202:209], v[72:75]
	v_mfma_f32_16x16x128_f8f6f4 v[68:71], v[0:7], v[210:217], v[68:71]
	v_mfma_f32_16x16x128_f8f6f4 v[56:59], v[8:15], v[210:217], v[56:59]
	v_mfma_f32_16x16x128_f8f6f4 v[52:55], v[0:7], v[218:225], v[52:55]
	v_mfma_f32_16x16x128_f8f6f4 v[40:43], v[8:15], v[218:225], v[40:43]
	s_setprio 0
	s_setprio 1
	v_mfma_f32_16x16x128_f8f6f4 v[80:83], v[16:23], v[194:201], v[80:83]
	v_mfma_f32_16x16x128_f8f6f4 v[76:79], v[24:31], v[194:201], v[76:79]
	v_mfma_f32_16x16x128_f8f6f4 v[64:67], v[16:23], v[202:209], v[64:67]
	v_mfma_f32_16x16x128_f8f6f4 v[60:63], v[24:31], v[202:209], v[60:63]
	v_mfma_f32_16x16x128_f8f6f4 v[48:51], v[16:23], v[210:217], v[48:51]
	v_mfma_f32_16x16x128_f8f6f4 v[44:47], v[24:31], v[210:217], v[44:47]
	v_mfma_f32_16x16x128_f8f6f4 v[36:39], v[16:23], v[218:225], v[36:39]
	v_mfma_f32_16x16x128_f8f6f4 v[32:35], v[24:31], v[218:225], v[32:35]
	s_setprio 0
	s_barrier
	s_add_u32 s97, s97, 0x100
	s_addc_u32 vcc_lo, vcc_lo, 0
	s_cmp_ge_i32 vcc_hi, s96
	s_mov_b64 s[58:59], s[60:61]
	s_mov_b32 s62, vcc_hi
	s_cbranch_scc0 .LBB0_1444
	s_nop 15
	s_nop 15
	s_and_b64 vcc, exec, s[94:95]
	s_cbranch_vccz .LBB0_1447
	s_barrier

.LBB0_1588:
	ds_read_b128 v[24:27], v218
	ds_read_b128 v[28:31], v218 offset:1024
	ds_read_b128 v[16:19], v218 offset:2048
	ds_read_b128 v[20:23], v218 offset:3072
	ds_read_b128 v[8:11], v219
	ds_read_b128 v[12:15], v219 offset:1024
	ds_read_b128 v[0:3], v219 offset:2048
	ds_read_b128 v[4:7], v219 offset:3072
	s_add_i32 s79, s52, 2
	s_add_u32 s53, s50, 0xfff80080
	s_addc_u32 s54, s51, -1
	s_cmp_eq_u32 s76, s52
	s_cselect_b32 s52, s75, s77
	s_cselect_b32 s55, s31, s54
	s_cselect_b32 s54, s37, s53
	s_cselect_b32 s53, s35, s78
	s_add_i32 m0, s47, 0xc000
	ds_read_b128 v[160:163], v220
	ds_read_b128 v[164:167], v220 offset:1024
	ds_read_b128 v[168:171], v220 offset:2048
	ds_read_b128 v[172:175], v220 offset:3072
	ds_read_b128 v[176:179], v220 offset:4096
	ds_read_b128 v[180:183], v220 offset:5120
	ds_read_b128 v[184:187], v220 offset:6144
	ds_read_b128 v[188:191], v220 offset:7168
	global_load_lds_dwordx4 v196, s[50:51]
	s_add_i32 m0, s47, 0xe000
	s_nop 0
	global_load_lds_dwordx4 v198, s[50:51]
	s_waitcnt vmcnt(8)
	s_waitcnt lgkmcnt(0)
	s_barrier
	s_setprio 1
	s_waitcnt lgkmcnt(0)
	v_mfma_f32_16x16x128_f8f6f4 v[156:159], v[24:31], v[160:167], v[156:159]
	v_mfma_f32_16x16x128_f8f6f4 v[152:155], v[16:23], v[160:167], v[152:155]
	v_mfma_f32_16x16x128_f8f6f4 v[148:151], v[24:31], v[168:175], v[148:151]
	v_mfma_f32_16x16x128_f8f6f4 v[140:143], v[16:23], v[168:175], v[140:143]
	v_mfma_f32_16x16x128_f8f6f4 v[132:135], v[24:31], v[176:183], v[132:135]
	v_mfma_f32_16x16x128_f8f6f4 v[124:127], v[16:23], v[176:183], v[124:127]
	v_mfma_f32_16x16x128_f8f6f4 v[116:119], v[24:31], v[184:191], v[116:119]
	v_mfma_f32_16x16x128_f8f6f4 v[108:111], v[16:23], v[184:191], v[108:111]
	s_setprio 0
	s_setprio 1
	v_mfma_f32_16x16x128_f8f6f4 v[144:147], v[8:15], v[160:167], v[144:147]
	v_mfma_f32_16x16x128_f8f6f4 v[136:139], v[0:7], v[160:167], v[136:139]
	v_mfma_f32_16x16x128_f8f6f4 v[128:131], v[8:15], v[168:175], v[128:131]
	v_mfma_f32_16x16x128_f8f6f4 v[120:123], v[0:7], v[168:175], v[120:123]
	v_mfma_f32_16x16x128_f8f6f4 v[112:115], v[8:15], v[176:183], v[112:115]
	v_mfma_f32_16x16x128_f8f6f4 v[104:107], v[0:7], v[176:183], v[104:107]
	v_mfma_f32_16x16x128_f8f6f4 v[100:103], v[8:15], v[184:191], v[100:103]
	v_mfma_f32_16x16x128_f8f6f4 v[96:99], v[0:7], v[184:191], v[96:99]
	s_setprio 0
	s_barrier
	s_add_i32 s80, s66, s93
	s_mov_b32 m0, s80
	ds_read_b128 v[168:171], v220 offset:16384
	ds_read_b128 v[172:175], v220 offset:17408
	ds_read_b128 v[176:179], v220 offset:18432
	ds_read_b128 v[180:183], v220 offset:19456
	ds_read_b128 v[184:187], v220 offset:20480
	ds_read_b128 v[188:191], v220 offset:21504
	ds_read_b128 v[202:205], v220 offset:22528
	ds_read_b128 v[206:209], v220 offset:23552
	global_load_lds_dwordx4 v192, s[52:53]
	s_add_i32 m0, s80, 0x2000
	s_add_u32 s80, s52, 0x80000
	v_lshl_add_u64 v[162:163], s[52:53], 0, v[194:195]
	s_addc_u32 s81, s53, 0
	s_add_i32 s82, s68, s93
	global_load_lds_dwordx4 v194, s[52:53]
	s_mov_b32 m0, s82
	v_lshl_add_u64 v[166:167], s[54:55], 0, v[194:195]
	global_load_lds_dwordx4 v192, s[80:81]
	s_add_i32 m0, s82, 0x2000
	s_nop 0
	global_load_lds_dwordx4 v194, s[80:81]
	v_lshl_add_u64 v[164:165], s[54:55], 0, v[192:193]
	s_mov_b32 m0, s47
	s_nop 0
	global_load_lds_dwordx4 v192, s[54:55]
	s_mov_b32 m0, s58
	s_nop 0
	global_load_lds_dwordx4 v194, s[54:55]
	s_waitcnt vmcnt(8)
	s_waitcnt lgkmcnt(0)
	s_barrier
	s_setprio 1
	s_waitcnt lgkmcnt(0)
	v_mfma_f32_16x16x128_f8f6f4 v[92:95], v[24:31], v[168:175], v[92:95]
	v_mfma_f32_16x16x128_f8f6f4 v[88:91], v[16:23], v[168:175], v[88:91]
	v_mfma_f32_16x16x128_f8f6f4 v[84:87], v[24:31], v[176:183], v[84:87]
	v_mfma_f32_16x16x128_f8f6f4 v[72:75], v[16:23], v[176:183], v[72:75]
	v_mfma_f32_16x16x128_f8f6f4 v[68:71], v[24:31], v[184:191], v[68:71]
	v_mfma_f32_16x16x128_f8f6f4 v[56:59], v[16:23], v[184:191], v[56:59]
	v_mfma_f32_16x16x128_f8f6f4 v[52:55], v[24:31], v[202:209], v[52:55]
	v_mfma_f32_16x16x128_f8f6f4 v[44:47], v[16:23], v[202:209], v[44:47]
	s_setprio 0
	s_setprio 1
	v_mfma_f32_16x16x128_f8f6f4 v[80:83], v[8:15], v[168:175], v[80:83]
	v_mfma_f32_16x16x128_f8f6f4 v[76:79], v[0:7], v[168:175], v[76:79]
	v_mfma_f32_16x16x128_f8f6f4 v[64:67], v[8:15], v[176:183], v[64:67]
	v_mfma_f32_16x16x128_f8f6f4 v[60:63], v[0:7], v[176:183], v[60:63]
	v_mfma_f32_16x16x128_f8f6f4 v[48:51], v[8:15], v[184:191], v[48:51]
	v_mfma_f32_16x16x128_f8f6f4 v[40:43], v[0:7], v[184:191], v[40:43]
	v_mfma_f32_16x16x128_f8f6f4 v[36:39], v[8:15], v[202:209], v[36:39]
	v_mfma_f32_16x16x128_f8f6f4 v[32:35], v[0:7], v[202:209], v[32:35]
	s_setprio 0
	s_barrier
	s_add_i32 s80, 0, 0x18000
	s_add_i32 s81, 0, 0x1c000
	v_add_u32_e32 v12, s80, v215
	v_add_u32_e32 v28, s81, v215
	ds_read_b128 v[0:3], v12
	ds_read_b128 v[4:7], v12 offset:1024
	ds_read_b128 v[8:11], v12 offset:2048
	ds_read_b128 v[12:15], v12 offset:3072
	ds_read_b128 v[16:19], v28
	ds_read_b128 v[20:23], v28 offset:1024
	ds_read_b128 v[24:27], v28 offset:2048
	ds_read_b128 v[28:31], v28 offset:3072
	s_add_u32 s54, s54, 0x80000
	s_addc_u32 s55, s55, 0
	s_mov_b32 m0, s59
	ds_read_b128 v[168:171], v220 offset:32768
	ds_read_b128 v[172:175], v220 offset:33792
	ds_read_b128 v[176:179], v220 offset:34816
	ds_read_b128 v[180:183], v220 offset:35840
	ds_read_b128 v[184:187], v220 offset:36864
	ds_read_b128 v[188:191], v220 offset:37888
	ds_read_b128 v[202:205], v220 offset:38912
	ds_read_b128 v[206:209], v220 offset:39936
	global_load_lds_dwordx4 v192, s[54:55]
	s_mov_b32 m0, s60
	s_nop 0
	global_load_lds_dwordx4 v194, s[54:55]
	s_waitcnt vmcnt(8)
	s_waitcnt lgkmcnt(0)
	s_barrier
	s_setprio 1
	s_waitcnt lgkmcnt(0)
	v_mfma_f32_16x16x128_f8f6f4 v[156:159], v[0:7], v[168:175], v[156:159]
	v_mfma_f32_16x16x128_f8f6f4 v[152:155], v[8:15], v[168:175], v[152:155]
	v_mfma_f32_16x16x128_f8f6f4 v[148:151], v[0:7], v[176:183], v[148:151]
	v_mfma_f32_16x16x128_f8f6f4 v[140:143], v[8:15], v[176:183], v[140:143]
	v_mfma_f32_16x16x128_f8f6f4 v[132:135], v[0:7], v[184:191], v[132:135]
	v_mfma_f32_16x16x128_f8f6f4 v[124:127], v[8:15], v[184:191], v[124:127]
	v_mfma_f32_16x16x128_f8f6f4 v[116:119], v[0:7], v[202:209], v[116:119]
	v_mfma_f32_16x16x128_f8f6f4 v[108:111], v[8:15], v[202:209], v[108:111]
	s_setprio 0
	s_setprio 1
	v_mfma_f32_16x16x128_f8f6f4 v[144:147], v[16:23], v[168:175], v[144:147]
	v_mfma_f32_16x16x128_f8f6f4 v[136:139], v[24:31], v[168:175], v[136:139]
	v_mfma_f32_16x16x128_f8f6f4 v[128:131], v[16:23], v[176:183], v[128:131]
	v_mfma_f32_16x16x128_f8f6f4 v[120:123], v[24:31], v[176:183], v[120:123]
	v_mfma_f32_16x16x128_f8f6f4 v[112:115], v[16:23], v[184:191], v[112:115]
	v_mfma_f32_16x16x128_f8f6f4 v[104:107], v[24:31], v[184:191], v[104:107]
	v_mfma_f32_16x16x128_f8f6f4 v[100:103], v[16:23], v[202:209], v[100:103]
	v_mfma_f32_16x16x128_f8f6f4 v[96:99], v[24:31], v[202:209], v[96:99]
	s_setprio 0
	s_barrier
	s_add_i32 s54, s80, s93
	s_add_i32 m0, s54, 0xffffff80
	ds_read_b128 v[168:171], v220 offset:49152
	ds_read_b128 v[172:175], v220 offset:50176
	ds_read_b128 v[176:179], v220 offset:51200
	ds_read_b128 v[180:183], v220 offset:52224
	ds_read_b128 v[184:187], v220 offset:53248
	ds_read_b128 v[188:191], v220 offset:54272
	ds_read_b128 v[202:205], v220 offset:55296
	ds_read_b128 v[206:209], v220 offset:56320
	global_load_lds_dwordx4 v192, s[52:53] offset:128
	s_add_i32 m0, s54, 0x2000
	s_add_u32 s52, s52, 0x80080
	v_lshl_add_u64 v[160:161], v[162:163], 0, s[24:25]
	s_addc_u32 s53, s53, 0
	s_add_i32 s54, s81, s93
	global_load_lds_dwordx4 v[160:161], off
	s_mov_b32 m0, s54
	s_nop 0
	global_load_lds_dwordx4 v192, s[52:53]
	s_add_i32 m0, s54, 0x2000
	s_nop 0
	global_load_lds_dwordx4 v194, s[52:53]
	v_lshl_add_u64 v[160:161], v[164:165], 0, s[24:25]
	s_mov_b32 m0, s64
	s_nop 0
	global_load_lds_dwordx4 v[160:161], off
	v_lshl_add_u64 v[160:161], v[166:167], 0, s[24:25]
	s_mov_b32 m0, s65
	s_nop 0
	global_load_lds_dwordx4 v[160:161], off
	s_waitcnt vmcnt(8)
	s_waitcnt lgkmcnt(0)
	s_barrier
	s_setprio 1
	s_waitcnt lgkmcnt(0)
	v_mfma_f32_16x16x128_f8f6f4 v[92:95], v[0:7], v[168:175], v[92:95]
	v_mfma_f32_16x16x128_f8f6f4 v[88:91], v[8:15], v[168:175], v[88:91]
	v_mfma_f32_16x16x128_f8f6f4 v[84:87], v[0:7], v[176:183], v[84:87]
	v_mfma_f32_16x16x128_f8f6f4 v[72:75], v[8:15], v[176:183], v[72:75]
	v_mfma_f32_16x16x128_f8f6f4 v[68:71], v[0:7], v[184:191], v[68:71]
	v_mfma_f32_16x16x128_f8f6f4 v[56:59], v[8:15], v[184:191], v[56:59]
	v_mfma_f32_16x16x128_f8f6f4 v[52:55], v[0:7], v[202:209], v[52:55]
	v_mfma_f32_16x16x128_f8f6f4 v[44:47], v[8:15], v[202:209], v[44:47]
	s_setprio 0
	s_setprio 1
	v_mfma_f32_16x16x128_f8f6f4 v[80:83], v[16:23], v[168:175], v[80:83]
	v_mfma_f32_16x16x128_f8f6f4 v[76:79], v[24:31], v[168:175], v[76:79]
	v_mfma_f32_16x16x128_f8f6f4 v[64:67], v[16:23], v[176:183], v[64:67]
	v_mfma_f32_16x16x128_f8f6f4 v[60:63], v[24:31], v[176:183], v[60:63]
	v_mfma_f32_16x16x128_f8f6f4 v[48:51], v[16:23], v[184:191], v[48:51]
	v_mfma_f32_16x16x128_f8f6f4 v[40:43], v[24:31], v[184:191], v[40:43]
	v_mfma_f32_16x16x128_f8f6f4 v[36:39], v[16:23], v[202:209], v[36:39]
	v_mfma_f32_16x16x128_f8f6f4 v[32:35], v[24:31], v[202:209], v[32:35]
	s_setprio 0
	s_barrier
	s_add_u32 s50, s50, 0x100
	s_addc_u32 s51, s51, 0
	s_add_u32 s77, s77, 0x100
	s_addc_u32 s78, s78, 0
	s_cmp_ge_i32 s79, s45
	s_mov_b32 s52, s79
	s_cbranch_scc0 .LBB0_1588
	s_nop 15
	s_nop 15
	s_andn2_b64 vcc, exec, s[48:49]
	s_cbranch_vccnz .LBB0_1602
	global_load_dword v0, v193, s[6:7] sc1
	s_waitcnt vmcnt(0)
	v_cmp_le_u32_e32 vcc, s88, v0
	s_cbranch_vccnz .LBB0_1601
	s_mov_b32 s31, 0x3ffff8
	s_branch .LBB0_1593
